# nt hint on the pool GEMM's once-read unshared A-operand (pbuf) LDS-DMA loads, on v23
# speedup vs baseline: 1.0095x; 1.0008x over previous
; #define G_STAGE_A(buf, h, b0, b1, tt) do { const bool _s2 = P::SEG && (tt) >= P::TS; \
;         const char* _g = _s2 ? (b1) + (ptrdiff_t)((tt) - P::TS) * kA2 + (ptrdiff_t)(h) * hA2 : (b0) + (ptrdiff_t)(tt) * kA + (ptrdiff_t)(h) * hA; \
;         stage2(lds + G_SA(buf, h) + ldsw, _g, _s2 ? voA20 : voA0, _s2 ? voA21 : voA1); } while (0)
; #define G_STAGE_B(buf, h, b0, b1, tt) do { const bool _s2 = P::SEG && (tt) >= P::TS; \
;         const char* _g = _s2 ? (b1) + (ptrdiff_t)((tt) - P::TS) * kB2 + (ptrdiff_t)(h) * hB2 : (b0) + (ptrdiff_t)(tt) * kB + (ptrdiff_t)(h) * hB; \
;         stage2(lds + G_SB(buf, h) + ldsw, _g, _s2 ? voB20 : voB0, _s2 ? voB21 : voB1); } while (0)
; #define G_WAIT_V(n) asm volatile("s_waitcnt vmcnt(" #n ")" ::: "memory")
; #define G_BAR __builtin_amdgcn_s_barrier()
; __device__ __forceinline__ bool order_mn(int L, int nM, int nN, int& pm, int& pn) {
;     const int nwg = nM * nN; if (L >= nwg) return false;
;     int wgid = L; { const int q = nwg / 8, r = nwg % 8, xcd = wgid % 8, off = wgid / 8; wgid = (xcd < r ? xcd * (q + 1) : r * (q + 1) + (xcd - r) * q) + off; }
;     const int nig = 8 * nN, gid = wgid / nig, fm = gid * 8, gsz = (nM - fm) < 8 ? (nM - fm) : 8;
;     pm = fm + ((wgid % nig) % gsz); pn = (wgid % nig) / gsz; return true;
; }
;     ...
;     const char* cA = p.a0(cur); const char* cB = p.b0(cur);
;     const char* cA2 = P::SEG ? p.a1(cur) : cA; const char* cB2 = P::SEG ? p.b1(cur) : cB;
;     G_STAGE_B(0, 0, cB, cB2, 0); G_STAGE_A(0, 0, cA, cA2, 0); G_STAGE_B(0, 1, cB, cB2, 0); G_STAGE_A(0, 1, cA, cA2, 0);
;     if (wr == 1) G_BAR;
;     G_WAIT_V(4); G_BAR;
;     G_STAGE_B(1, 0, cB, cB2, 1); G_STAGE_A(1, 0, cA, cA2, 1); G_STAGE_B(1, 1, cB, cB2, 1);
;     G_WAIT_V(6); G_BAR;
.LBB0_1660:
	s_cmp_lt_i32 s74, 15
	s_cselect_b64 s[0:1], -1, 0
	s_cmp_gt_i32 s75, 14
	s_cselect_b64 s[2:3], -1, 0
	s_and_b64 s[0:1], s[0:1], s[2:3]
	s_andn2_b64 vcc, exec, s[0:1]
	s_cbranch_vccnz .LBB0_1775
	s_mov_b64 s[0:1], s[72:73]
	v_mov_b32_e32 v0, v220
	s_load_dwordx2 s[0:1], s[0:1], 0xa0
	s_add_i32 s2, 0, 0x2080c
	v_mov_b32_e32 v0, s2
	ds_read_b32 v0, v0
	s_movk_i32 s2, 0x1ff
	s_waitcnt vmcnt(0)
	v_mov_b32_e32 v8, v220
	s_waitcnt lgkmcnt(0)
	v_cmp_lt_i32_e32 vcc, s2, v0
	v_readfirstlane_b32 s30, v0
	v_readfirstlane_b32 s31, v8
	s_cbranch_vccnz .LBB0_1689
	v_lshlrev_b32_e32 v0, 4, v8
	v_add_u32_e32 v1, 0x2000, v0
	v_ashrrev_i32_e32 v2, 31, v1
	v_lshrrev_b32_e32 v2, 22, v2
	v_add_u32_e32 v2, v1, v2
	v_ashrrev_i32_e32 v2, 10, v2
	v_mul_i32_i24_e32 v3, 0x400, v2
	v_sub_u32_e32 v1, v1, v3
	v_lshrrev_b32_e32 v3, 4, v1
	v_bitop3_b32 v1, v3, v1, 32 bitop3:0x6c
	v_ashrrev_i32_e32 v3, 31, v1
	v_lshrrev_b32_e32 v3, 26, v3
	v_add_u32_e32 v3, v1, v3
	v_lshlrev_b32_e32 v5, 3, v2
	v_ashrrev_i32_e32 v4, 6, v3
	v_and_b32_e32 v5, -16, v5
	v_and_b32_e32 v3, 0xc0, v3
	v_add_u32_e32 v5, v4, v5
	v_sub_u32_e32 v1, v1, v3
	v_mov_b32_e32 v3, 1
	v_and_b32_e32 v4, 3, v4
	s_mov_b32 s2, 0x7fffe0
	v_lshrrev_b32_e32 v6, 2, v5
	v_lshlrev_b32_e32 v7, 1, v5
	v_lshlrev_b32_e32 v2, 5, v2
	v_ashrrev_i16_sdwa v1, v3, sext(v1) dst_sel:DWORD dst_unused:UNUSED_PAD src0_sel:DWORD src1_sel:BYTE_0
	v_and_or_b32 v4, v5, s2, v4
	v_and_b32_e32 v6, 4, v6
	v_and_b32_e32 v7, 24, v7
	v_and_b32_e32 v2, 32, v2
	v_bfe_i32 v1, v1, 0, 16
	v_or3_b32 v4, v4, v6, v7
	v_add_lshl_u32 v1, v2, v1, 1
	v_lshl_add_u32 v144, v4, 9, v1
	v_lshl_add_u32 v146, v5, 11, v1
	v_bfe_i32 v1, v8, 27, 1
	v_lshrrev_b32_e32 v1, 22, v1
	v_add_u32_e32 v1, v0, v1
	v_and_b32_e32 v1, 0xfffffc00, v1
	v_sub_u32_e32 v0, v0, v1
	v_ashrrev_i32_e32 v2, 31, v8
	v_lshrrev_b32_e32 v1, 4, v0
	v_lshrrev_b32_e32 v2, 26, v2
	v_bitop3_b32 v1, v1, v0, 32 bitop3:0x6c
	v_ashrrev_i32_e32 v0, 31, v0
	v_add_u32_e32 v2, v8, v2
	v_lshrrev_b32_e32 v0, 26, v0
	v_ashrrev_i32_e32 v2, 6, v2
	s_add_u32 s33, s0, 0x4000000
	v_add_u32_e32 v0, v1, v0
	v_lshlrev_b32_e32 v4, 3, v2
	s_addc_u32 s34, s1, 0
	v_ashrrev_i32_e32 v0, 6, v0
	v_and_b32_e32 v4, -16, v4
	s_add_u32 s35, s0, 0x10480000
	v_add_u32_e32 v4, v0, v4
	v_and_b32_e32 v5, 3, v0
	s_addc_u32 s36, s1, 0
	v_and_or_b32 v5, v4, s2, v5
	s_ashr_i32 s2, s30, 31
	s_lshr_b32 s2, s2, 29
	s_add_i32 s2, s30, s2
	s_ashr_i32 s3, s2, 3
	s_and_b32 s2, s2, -8
	s_sub_i32 s2, s30, s2
	s_lshr_b32 s4, s2, 31
	s_or_b32 s4, s4, 64
	s_mul_i32 s2, s4, s2
	s_add_i32 s2, s2, s3
	s_ashr_i32 s3, s2, 31
	s_lshr_b32 s3, s3, 27
	s_add_i32 s3, s2, s3
	v_mul_i32_i24_e32 v0, 64, v0
	s_ashr_i32 s4, s3, 5
	v_sub_u32_e32 v0, v1, v0
	s_lshl_b32 s7, s4, 3
	v_lshlrev_b32_e32 v2, 5, v2
	v_ashrrev_i16_sdwa v0, v3, sext(v0) dst_sel:DWORD dst_unused:UNUSED_PAD src0_sel:DWORD src1_sel:BYTE_0
	s_sub_i32 s4, 0x80, s7
	v_and_b32_e32 v2, 32, v2
	v_bfe_i32 v0, v0, 0, 16
	s_min_u32 s8, s4, 8
	s_andn2_b32 s3, s3, 31
	v_add_lshl_u32 v0, v2, v0, 1
	s_sub_i32 s9, s2, s3
	v_cvt_f32_ubyte0_e32 v2, s8
	v_cvt_f32_i32_e32 v1, s9
	v_rcp_iflag_f32_e32 v3, v2
	v_lshrrev_b32_e32 v6, 2, v4
	v_lshlrev_b32_e32 v7, 1, v4
	v_and_b32_e32 v6, 4, v6
	v_and_b32_e32 v7, 24, v7
	v_or3_b32 v5, v5, v6, v7
	v_lshl_add_u32 v148, v5, 9, v0
	v_lshl_add_u32 v150, v4, 11, v0
	v_mul_f32_e32 v0, v1, v3
	v_trunc_f32_e32 v0, v0
	v_fma_f32 v1, -v0, v2, v1
	v_cvt_i32_f32_e32 v0, v0
	s_ashr_i32 s6, s31, 6
	s_ashr_i32 s2, s9, 30
	s_ashr_i32 s5, s31, 8
	s_lshl_b32 s37, s6, 10
	s_or_b32 s4, s2, 1
	v_cmp_ge_f32_e64 s[2:3], |v1|, v2
	s_and_b64 s[2:3], s[2:3], exec
	s_cselect_b32 s2, s4, 0
	v_readfirstlane_b32 s3, v0
	s_add_i32 s4, s3, s2
	s_mul_i32 s2, s4, s8
	s_sub_i32 s2, s9, s2
	s_sext_i32_i8 s2, s2
	s_add_i32 s8, s7, s2
	s_bfe_i64 s[2:3], s[4:5], 0x80000
	s_ashr_i32 s9, s8, 31
	s_lshl_b64 s[10:11], s[2:3], 9
	s_lshl_b64 s[12:13], s[8:9], 19
	s_add_u32 s7, s33, s12
	s_addc_u32 s9, s34, s13
	s_add_u32 s24, s7, s10
	s_addc_u32 s25, s9, s11
	s_lshl_b64 s[2:3], s[2:3], 17
	s_add_u32 s26, s35, s2
	s_addc_u32 s27, s36, s3
	s_add_i32 s38, s37, 0
	v_ashrrev_i32_e32 v149, 31, v148
	s_add_i32 m0, s38, 0x10000
	v_lshl_add_u64 v[0:1], s[26:27], 0, v[148:149]
	v_ashrrev_i32_e32 v145, 31, v144
	global_load_lds_dwordx4 v[0:1], off
	v_lshl_add_u64 v[2:3], s[26:27], 0, v[144:145]
	s_add_i32 m0, s38, 0x12000
	v_ashrrev_i32_e32 v151, 31, v150
	s_add_i32 s39, s38, 0x2000
	global_load_lds_dwordx4 v[2:3], off
	v_lshl_add_u64 v[4:5], s[24:25], 0, v[150:151]
	s_mov_b32 m0, s38
	v_ashrrev_i32_e32 v147, 31, v146
	s_add_u32 s2, s26, 0x10000
	global_load_lds_dwordx4 v[4:5], off nt
	v_lshl_add_u64 v[6:7], s[24:25], 0, v[146:147]
	s_mov_b32 m0, s39
	s_addc_u32 s3, s27, 0
	global_load_lds_dwordx4 v[6:7], off nt
	s_add_i32 m0, s38, 0x14000
	v_lshl_add_u64 v[10:11], s[2:3], 0, v[148:149]
	global_load_lds_dwordx4 v[10:11], off
	s_add_i32 m0, s38, 0x16000
	v_lshl_add_u64 v[10:11], s[2:3], 0, v[144:145]
	s_add_u32 s2, s24, 0x40000
	s_addc_u32 s3, s25, 0
	s_add_i32 s40, s38, 0x4000
	global_load_lds_dwordx4 v[10:11], off
	v_lshl_add_u64 v[10:11], s[2:3], 0, v[150:151]
	s_mov_b32 m0, s40
	s_add_i32 s41, s38, 0x6000
	global_load_lds_dwordx4 v[10:11], off nt
	v_lshl_add_u64 v[10:11], s[2:3], 0, v[146:147]
	s_mov_b32 m0, s41
	global_load_lds_dwordx4 v[10:11], off nt
	s_and_b32 s42, s6, 3
	s_mov_b64 s[6:7], 0x80
	s_add_i32 m0, s38, 0x18000
	v_lshl_add_u64 v[0:1], v[0:1], 0, s[6:7]
	global_load_lds_dwordx4 v[0:1], off
	v_lshl_add_u64 v[0:1], v[2:3], 0, s[6:7]
	s_add_i32 m0, s38, 0x1a000
	s_add_i32 s43, s38, 0x8000
	s_add_i32 s44, s38, 0xa000
	global_load_lds_dwordx4 v[0:1], off
	v_lshl_add_u64 v[0:1], v[4:5], 0, s[6:7]
	s_mov_b32 m0, s43
	s_add_u32 s10, s26, 0x10080
	global_load_lds_dwordx4 v[0:1], off nt
	v_lshl_add_u64 v[0:1], v[6:7], 0, s[6:7]
	s_mov_b32 m0, s44
	s_addc_u32 s11, s27, 0
	global_load_lds_dwordx4 v[0:1], off nt
	s_add_i32 m0, s38, 0x1c000
	v_lshl_add_u64 v[0:1], s[10:11], 0, v[148:149]
	global_load_lds_dwordx4 v[0:1], off
	v_lshl_add_u64 v[0:1], s[10:11], 0, v[144:145]
	s_add_i32 m0, s38, 0x1e000
	s_add_i32 s49, 0, 0x10000
	global_load_lds_dwordx4 v[0:1], off
	s_cmp_lg_u32 s5, 1
	s_cbranch_scc1 .LBB0_1664
	s_barrier

.LBB0_1670:
	s_waitcnt lgkmcnt(0)
	ds_read_b128 v[0:3], v173
	ds_read_b128 v[4:7], v173 offset:1024
	ds_read_b128 v[8:11], v173 offset:2048
	ds_read_b128 v[12:15], v173 offset:3072
	s_lshl_b64 s[22:23], s[16:17], 17
	s_add_u32 s22, s35, s22
	s_addc_u32 s23, s36, s23
	s_add_u32 s52, s24, 0x40080
	s_addc_u32 s53, s25, 0
	s_mov_b32 m0, s47
	v_lshl_add_u64 v[48:49], s[52:53], 0, v[150:151]
	ds_read_b128 v[16:19], v174
	ds_read_b128 v[20:23], v174 offset:1024
	ds_read_b128 v[24:27], v174 offset:2048
	ds_read_b128 v[28:31], v174 offset:3072
	ds_read_b128 v[32:35], v174 offset:4096
	ds_read_b128 v[36:39], v174 offset:5120
	ds_read_b128 v[40:43], v174 offset:6144
	ds_read_b128 v[44:47], v174 offset:7168
	global_load_lds_dwordx4 v[48:49], off nt
	s_mov_b32 m0, s48
	v_lshl_add_u64 v[48:49], s[52:53], 0, v[146:147]
	global_load_lds_dwordx4 v[48:49], off nt
	s_waitcnt lgkmcnt(8)
	s_barrier
	s_waitcnt lgkmcnt(0)
	v_mfma_f32_16x16x32_bf16 v[48:51], v[0:3], v[16:19], 0
	v_mfma_f32_16x16x32_bf16 v[52:55], v[8:11], v[16:19], 0
	v_mfma_f32_16x16x32_bf16 v[56:59], v[0:3], v[24:27], 0
	v_mfma_f32_16x16x32_bf16 v[60:63], v[8:11], v[24:27], 0
	v_mfma_f32_16x16x32_bf16 v[64:67], v[0:3], v[32:35], 0
	v_mfma_f32_16x16x32_bf16 v[68:71], v[8:11], v[32:35], 0
	v_mfma_f32_16x16x32_bf16 v[72:75], v[0:3], v[40:43], 0
	v_mfma_f32_16x16x32_bf16 v[76:79], v[8:11], v[40:43], 0
	v_mfma_f32_16x16x32_bf16 v[48:51], v[4:7], v[20:23], v[48:51]
	v_mfma_f32_16x16x32_bf16 v[52:55], v[12:15], v[20:23], v[52:55]
	v_mfma_f32_16x16x32_bf16 v[56:59], v[4:7], v[28:31], v[56:59]
	v_mfma_f32_16x16x32_bf16 v[60:63], v[12:15], v[28:31], v[60:63]
	v_mfma_f32_16x16x32_bf16 v[64:67], v[4:7], v[36:39], v[64:67]
	v_mfma_f32_16x16x32_bf16 v[68:71], v[12:15], v[36:39], v[68:71]
	v_mfma_f32_16x16x32_bf16 v[72:75], v[4:7], v[44:47], v[72:75]
	v_mfma_f32_16x16x32_bf16 v[76:79], v[12:15], v[44:47], v[76:79]
	s_barrier
	v_lshl_add_u64 v[168:169], s[26:27], 0, v[148:149]
	s_mov_b32 m0, s49
	v_lshl_add_u64 v[96:97], v[168:169], 0, s[10:11]
	v_lshl_add_u64 v[212:213], s[26:27], 0, v[144:145]
	ds_read_b128 v[80:83], v175
	ds_read_b128 v[84:87], v175 offset:1024
	ds_read_b128 v[88:91], v175 offset:2048
	ds_read_b128 v[92:95], v175 offset:3072
	global_load_lds_dwordx4 v[96:97], off
	s_mov_b32 m0, s50
	v_lshl_add_u64 v[96:97], v[212:213], 0, s[10:11]
	global_load_lds_dwordx4 v[96:97], off
	s_barrier
	s_waitcnt lgkmcnt(0)
	v_mfma_f32_16x16x32_bf16 v[96:99], v[80:83], v[16:19], 0
	v_mfma_f32_16x16x32_bf16 v[16:19], v[88:91], v[16:19], 0
	v_mfma_f32_16x16x32_bf16 v[100:103], v[80:83], v[24:27], 0
	v_mfma_f32_16x16x32_bf16 v[24:27], v[88:91], v[24:27], 0
	v_mfma_f32_16x16x32_bf16 v[104:107], v[80:83], v[32:35], 0
	v_mfma_f32_16x16x32_bf16 v[32:35], v[88:91], v[32:35], 0
	v_mfma_f32_16x16x32_bf16 v[108:111], v[80:83], v[40:43], 0
	v_mfma_f32_16x16x32_bf16 v[40:43], v[88:91], v[40:43], 0
	v_mfma_f32_16x16x32_bf16 v[96:99], v[84:87], v[20:23], v[96:99]
	v_mfma_f32_16x16x32_bf16 v[16:19], v[92:95], v[20:23], v[16:19]
	v_mfma_f32_16x16x32_bf16 v[20:23], v[84:87], v[28:31], v[100:103]
	v_mfma_f32_16x16x32_bf16 v[24:27], v[92:95], v[28:31], v[24:27]
	v_mfma_f32_16x16x32_bf16 v[28:31], v[84:87], v[36:39], v[104:107]
	v_mfma_f32_16x16x32_bf16 v[32:35], v[92:95], v[36:39], v[32:35]
	v_mfma_f32_16x16x32_bf16 v[36:39], v[84:87], v[44:47], v[108:111]
	v_mfma_f32_16x16x32_bf16 v[40:43], v[92:95], v[44:47], v[40:43]
	v_lshl_add_u64 v[214:215], s[24:25], 0, v[150:151]
	s_mov_b32 m0, s38
	v_lshl_add_u64 v[128:129], v[214:215], 0, s[10:11]
	v_lshl_add_u64 v[216:217], s[24:25], 0, v[146:147]
	s_barrier
	ds_read_b128 v[44:47], v174 offset:16384
	ds_read_b128 v[100:103], v174 offset:17408
	ds_read_b128 v[104:107], v174 offset:18432
	ds_read_b128 v[108:111], v174 offset:19456
	ds_read_b128 v[112:115], v174 offset:20480
	ds_read_b128 v[116:119], v174 offset:21504
	ds_read_b128 v[120:123], v174 offset:22528
	ds_read_b128 v[124:127], v174 offset:23552
	global_load_lds_dwordx4 v[128:129], off nt
	s_mov_b32 m0, s39
	v_lshl_add_u64 v[128:129], v[216:217], 0, s[10:11]
	global_load_lds_dwordx4 v[128:129], off nt
	s_barrier
	s_waitcnt lgkmcnt(0)
	v_mfma_f32_16x16x32_bf16 v[128:131], v[0:3], v[44:47], 0
	v_mfma_f32_16x16x32_bf16 v[132:135], v[8:11], v[44:47], 0
	v_mfma_f32_16x16x32_bf16 v[136:139], v[0:3], v[104:107], 0
	v_mfma_f32_16x16x32_bf16 v[140:143], v[8:11], v[104:107], 0
	v_mfma_f32_16x16x32_bf16 v[152:155], v[0:3], v[112:115], 0
	v_mfma_f32_16x16x32_bf16 v[156:159], v[8:11], v[112:115], 0
	v_mfma_f32_16x16x32_bf16 v[0:3], v[0:3], v[120:123], 0
	v_mfma_f32_16x16x32_bf16 v[8:11], v[8:11], v[120:123], 0
	v_mfma_f32_16x16x32_bf16 v[128:131], v[4:7], v[100:103], v[128:131]
	v_mfma_f32_16x16x32_bf16 v[136:139], v[4:7], v[108:111], v[136:139]
	v_mfma_f32_16x16x32_bf16 v[140:143], v[12:15], v[108:111], v[140:143]
	v_mfma_f32_16x16x32_bf16 v[152:155], v[4:7], v[116:119], v[152:155]
	v_mfma_f32_16x16x32_bf16 v[156:159], v[12:15], v[116:119], v[156:159]
	v_mfma_f32_16x16x32_bf16 v[0:3], v[4:7], v[124:127], v[0:3]
	v_mfma_f32_16x16x32_bf16 v[4:7], v[12:15], v[124:127], v[8:11]
	v_mfma_f32_16x16x32_bf16 v[132:135], v[12:15], v[100:103], v[132:135]
	s_barrier
	s_add_u32 s52, s26, 0x10100
	s_addc_u32 s53, s27, 0
	s_add_i32 s19, s46, s37
	v_lshl_add_u64 v[8:9], s[52:53], 0, v[148:149]
	s_mov_b32 m0, s19
	s_add_i32 s17, s19, 0x2000
	global_load_lds_dwordx4 v[8:9], off
	s_mov_b32 m0, s17
	v_lshl_add_u64 v[8:9], s[52:53], 0, v[144:145]
	global_load_lds_dwordx4 v[8:9], off
	s_waitcnt vmcnt(6)
	s_barrier
	v_mfma_f32_16x16x32_bf16 v[8:11], v[80:83], v[44:47], 0
	v_mfma_f32_16x16x32_bf16 v[12:15], v[88:91], v[44:47], 0
	v_mfma_f32_16x16x32_bf16 v[44:47], v[80:83], v[104:107], 0
	v_mfma_f32_16x16x32_bf16 v[104:107], v[88:91], v[104:107], 0
	v_mfma_f32_16x16x32_bf16 v[160:163], v[80:83], v[112:115], 0
	v_mfma_f32_16x16x32_bf16 v[112:115], v[88:91], v[112:115], 0
	v_mfma_f32_16x16x32_bf16 v[80:83], v[80:83], v[120:123], 0
	v_mfma_f32_16x16x32_bf16 v[88:91], v[88:91], v[120:123], 0
	v_mfma_f32_16x16x32_bf16 v[8:11], v[84:87], v[100:103], v[8:11]
	v_mfma_f32_16x16x32_bf16 v[12:15], v[92:95], v[100:103], v[12:15]
	v_mfma_f32_16x16x32_bf16 v[44:47], v[84:87], v[108:111], v[44:47]
	v_mfma_f32_16x16x32_bf16 v[100:103], v[92:95], v[108:111], v[104:107]
	v_mfma_f32_16x16x32_bf16 v[104:107], v[84:87], v[116:119], v[160:163]
	v_mfma_f32_16x16x32_bf16 v[108:111], v[92:95], v[116:119], v[112:115]
	v_mfma_f32_16x16x32_bf16 v[80:83], v[84:87], v[124:127], v[80:83]
	v_mfma_f32_16x16x32_bf16 v[84:87], v[92:95], v[124:127], v[88:91]
	s_add_i32 s51, 0, 0x18000
	v_add_u32_e32 v221, s51, v171
	s_barrier
	ds_read_b128 v[88:91], v221
	ds_read_b128 v[92:95], v221 offset:1024
	ds_read_b128 v[112:115], v221 offset:2048
	ds_read_b128 v[116:119], v221 offset:3072
	s_add_u32 s52, s24, 0x40100
	s_addc_u32 s53, s25, 0
	s_mov_b32 m0, s40
	v_lshl_add_u64 v[196:197], s[52:53], 0, v[150:151]
	ds_read_b128 v[120:123], v174 offset:32768
	ds_read_b128 v[124:127], v174 offset:33792
	ds_read_b128 v[160:163], v174 offset:34816
	ds_read_b128 v[164:167], v174 offset:35840
	ds_read_b128 v[180:183], v174 offset:36864
	ds_read_b128 v[184:187], v174 offset:37888
	ds_read_b128 v[188:191], v174 offset:38912
	ds_read_b128 v[192:195], v174 offset:39936
	global_load_lds_dwordx4 v[196:197], off nt
	s_mov_b32 m0, s41
	v_lshl_add_u64 v[196:197], s[52:53], 0, v[146:147]
	global_load_lds_dwordx4 v[196:197], off nt
	s_waitcnt lgkmcnt(8)
	s_barrier
	s_waitcnt lgkmcnt(0)
	v_mfma_f32_16x16x32_bf16 v[48:51], v[88:91], v[120:123], v[48:51]
	v_mfma_f32_16x16x32_bf16 v[52:55], v[112:115], v[120:123], v[52:55]
	v_mfma_f32_16x16x32_bf16 v[56:59], v[88:91], v[160:163], v[56:59]
	v_mfma_f32_16x16x32_bf16 v[60:63], v[112:115], v[160:163], v[60:63]
	v_mfma_f32_16x16x32_bf16 v[64:67], v[88:91], v[180:183], v[64:67]
	v_mfma_f32_16x16x32_bf16 v[68:71], v[112:115], v[180:183], v[68:71]
	v_mfma_f32_16x16x32_bf16 v[72:75], v[88:91], v[188:191], v[72:75]
	v_mfma_f32_16x16x32_bf16 v[76:79], v[112:115], v[188:191], v[76:79]
	v_mfma_f32_16x16x32_bf16 v[48:51], v[92:95], v[124:127], v[48:51]
	v_mfma_f32_16x16x32_bf16 v[52:55], v[116:119], v[124:127], v[52:55]
	v_mfma_f32_16x16x32_bf16 v[56:59], v[92:95], v[164:167], v[56:59]
	v_mfma_f32_16x16x32_bf16 v[60:63], v[116:119], v[164:167], v[60:63]
	v_mfma_f32_16x16x32_bf16 v[64:67], v[92:95], v[184:187], v[64:67]
	v_mfma_f32_16x16x32_bf16 v[68:71], v[116:119], v[184:187], v[68:71]
	v_mfma_f32_16x16x32_bf16 v[72:75], v[92:95], v[192:195], v[72:75]
	v_mfma_f32_16x16x32_bf16 v[76:79], v[116:119], v[192:195], v[76:79]
	s_barrier
	s_add_i32 s54, 0, 0x1c000
	s_add_i32 s53, s51, s37
	v_add_u32_e32 v226, s54, v171
	v_lshl_add_u64 v[168:169], v[168:169], 0, s[12:13]
	s_mov_b32 m0, s53
	s_add_i32 s51, s53, 0x2000
	ds_read_b128 v[196:199], v226
	ds_read_b128 v[200:203], v226 offset:1024
	ds_read_b128 v[204:207], v226 offset:2048
	ds_read_b128 v[208:211], v226 offset:3072
	global_load_lds_dwordx4 v[168:169], off
	s_mov_b32 m0, s51
	v_lshl_add_u64 v[168:169], v[212:213], 0, s[12:13]
	global_load_lds_dwordx4 v[168:169], off
	s_barrier
	s_waitcnt lgkmcnt(0)
	v_mfma_f32_16x16x32_bf16 v[96:99], v[196:199], v[120:123], v[96:99]
	v_mfma_f32_16x16x32_bf16 v[16:19], v[204:207], v[120:123], v[16:19]
	v_mfma_f32_16x16x32_bf16 v[20:23], v[196:199], v[160:163], v[20:23]
	v_mfma_f32_16x16x32_bf16 v[24:27], v[204:207], v[160:163], v[24:27]
	v_mfma_f32_16x16x32_bf16 v[28:31], v[196:199], v[180:183], v[28:31]
	v_mfma_f32_16x16x32_bf16 v[32:35], v[204:207], v[180:183], v[32:35]
	v_mfma_f32_16x16x32_bf16 v[36:39], v[196:199], v[188:191], v[36:39]
	v_mfma_f32_16x16x32_bf16 v[40:43], v[204:207], v[188:191], v[40:43]
	v_mfma_f32_16x16x32_bf16 v[96:99], v[200:203], v[124:127], v[96:99]
	v_mfma_f32_16x16x32_bf16 v[16:19], v[208:211], v[124:127], v[16:19]
	v_mfma_f32_16x16x32_bf16 v[20:23], v[200:203], v[164:167], v[20:23]
	v_mfma_f32_16x16x32_bf16 v[24:27], v[208:211], v[164:167], v[24:27]
	v_mfma_f32_16x16x32_bf16 v[28:31], v[200:203], v[184:187], v[28:31]
	v_mfma_f32_16x16x32_bf16 v[32:35], v[208:211], v[184:187], v[32:35]
	v_mfma_f32_16x16x32_bf16 v[36:39], v[200:203], v[192:195], v[36:39]
	v_mfma_f32_16x16x32_bf16 v[40:43], v[208:211], v[192:195], v[40:43]
	s_mov_b32 m0, s43
	v_lshl_add_u64 v[168:169], v[214:215], 0, s[12:13]
	s_barrier
	ds_read_b128 v[120:123], v174 offset:49152
	ds_read_b128 v[124:127], v174 offset:50176
	ds_read_b128 v[160:163], v174 offset:51200
	ds_read_b128 v[164:167], v174 offset:52224
	ds_read_b128 v[180:183], v174 offset:53248
	ds_read_b128 v[184:187], v174 offset:54272
	ds_read_b128 v[188:191], v174 offset:55296
	ds_read_b128 v[192:195], v174 offset:56320
	global_load_lds_dwordx4 v[168:169], off nt
	s_mov_b32 m0, s44
	v_lshl_add_u64 v[168:169], v[216:217], 0, s[12:13]
	global_load_lds_dwordx4 v[168:169], off nt
	s_barrier
	s_waitcnt lgkmcnt(0)
	v_mfma_f32_16x16x32_bf16 v[128:131], v[88:91], v[120:123], v[128:131]
	v_mfma_f32_16x16x32_bf16 v[132:135], v[112:115], v[120:123], v[132:135]
	v_mfma_f32_16x16x32_bf16 v[136:139], v[88:91], v[160:163], v[136:139]
	v_mfma_f32_16x16x32_bf16 v[140:143], v[112:115], v[160:163], v[140:143]
	v_mfma_f32_16x16x32_bf16 v[152:155], v[88:91], v[180:183], v[152:155]
	v_mfma_f32_16x16x32_bf16 v[156:159], v[112:115], v[180:183], v[156:159]
	v_mfma_f32_16x16x32_bf16 v[0:3], v[88:91], v[188:191], v[0:3]
	v_mfma_f32_16x16x32_bf16 v[4:7], v[112:115], v[188:191], v[4:7]
	v_mfma_f32_16x16x32_bf16 v[88:91], v[92:95], v[124:127], v[128:131]
	v_mfma_f32_16x16x32_bf16 v[112:115], v[116:119], v[124:127], v[132:135]
	v_mfma_f32_16x16x32_bf16 v[128:131], v[92:95], v[164:167], v[136:139]
	v_mfma_f32_16x16x32_bf16 v[132:135], v[116:119], v[164:167], v[140:143]
	v_mfma_f32_16x16x32_bf16 v[136:139], v[92:95], v[184:187], v[152:155]
	v_mfma_f32_16x16x32_bf16 v[140:143], v[116:119], v[184:187], v[156:159]
	v_mfma_f32_16x16x32_bf16 v[0:3], v[92:95], v[192:195], v[0:3]
	v_mfma_f32_16x16x32_bf16 v[4:7], v[116:119], v[192:195], v[4:7]
	s_barrier
	s_add_u32 s56, s26, 0x10180
	s_addc_u32 s57, s27, 0
	s_add_i32 s54, s54, s37
	v_lshl_add_u64 v[92:93], s[56:57], 0, v[148:149]
	s_mov_b32 m0, s54
	s_add_i32 s52, s54, 0x2000
	global_load_lds_dwordx4 v[92:93], off
	s_mov_b32 m0, s52
	v_lshl_add_u64 v[92:93], s[56:57], 0, v[144:145]
	global_load_lds_dwordx4 v[92:93], off
	s_waitcnt vmcnt(6)
	s_barrier
	v_mfma_f32_16x16x32_bf16 v[8:11], v[196:199], v[120:123], v[8:11]
	s_and_b64 s[28:29], s[28:29], exec
	s_cselect_b32 s27, s23, s27
	s_cselect_b32 s26, s22, s26
	v_mfma_f32_16x16x32_bf16 v[12:15], v[204:207], v[120:123], v[12:15]
	v_mfma_f32_16x16x32_bf16 v[44:47], v[196:199], v[160:163], v[44:47]
	v_mfma_f32_16x16x32_bf16 v[92:95], v[204:207], v[160:163], v[100:103]
	v_mfma_f32_16x16x32_bf16 v[100:103], v[196:199], v[180:183], v[104:107]
	v_mfma_f32_16x16x32_bf16 v[104:107], v[204:207], v[180:183], v[108:111]
	v_mfma_f32_16x16x32_bf16 v[80:83], v[196:199], v[188:191], v[80:83]
	v_mfma_f32_16x16x32_bf16 v[84:87], v[204:207], v[188:191], v[84:87]
	v_mfma_f32_16x16x32_bf16 v[8:11], v[200:203], v[124:127], v[8:11]
	v_mfma_f32_16x16x32_bf16 v[12:15], v[208:211], v[124:127], v[12:15]
	v_mfma_f32_16x16x32_bf16 v[44:47], v[200:203], v[164:167], v[44:47]
	v_mfma_f32_16x16x32_bf16 v[92:95], v[208:211], v[164:167], v[92:95]
	v_mfma_f32_16x16x32_bf16 v[100:103], v[200:203], v[184:187], v[100:103]
	v_mfma_f32_16x16x32_bf16 v[104:107], v[208:211], v[184:187], v[104:107]
	v_mfma_f32_16x16x32_bf16 v[80:83], v[200:203], v[192:195], v[80:83]
	v_mfma_f32_16x16x32_bf16 v[84:87], v[208:211], v[192:195], v[84:87]
	s_barrier
	ds_read_b128 v[108:111], v173
	ds_read_b128 v[116:119], v173 offset:1024
	ds_read_b128 v[120:123], v173 offset:2048
	ds_read_b128 v[124:127], v173 offset:3072
	s_add_u32 s24, s24, 0x40180
	s_addc_u32 s25, s25, 0
	s_mov_b32 m0, s47
	v_lshl_add_u64 v[168:169], s[24:25], 0, v[150:151]
	ds_read_b128 v[152:155], v174
	ds_read_b128 v[156:159], v174 offset:1024
	ds_read_b128 v[160:163], v174 offset:2048
	ds_read_b128 v[164:167], v174 offset:3072
	ds_read_b128 v[180:183], v174 offset:4096
	ds_read_b128 v[184:187], v174 offset:5120
	ds_read_b128 v[188:191], v174 offset:6144
	ds_read_b128 v[192:195], v174 offset:7168
	global_load_lds_dwordx4 v[168:169], off nt
	s_mov_b32 m0, s48
	v_lshl_add_u64 v[168:169], s[24:25], 0, v[146:147]
	global_load_lds_dwordx4 v[168:169], off nt
	s_waitcnt lgkmcnt(8)
	s_barrier
	s_waitcnt lgkmcnt(0)
	v_mfma_f32_16x16x32_bf16 v[48:51], v[108:111], v[152:155], v[48:51]
	v_mfma_f32_16x16x32_bf16 v[52:55], v[120:123], v[152:155], v[52:55]
	v_mfma_f32_16x16x32_bf16 v[56:59], v[108:111], v[160:163], v[56:59]
	v_mfma_f32_16x16x32_bf16 v[60:63], v[120:123], v[160:163], v[60:63]
	v_mfma_f32_16x16x32_bf16 v[64:67], v[108:111], v[180:183], v[64:67]
	v_mfma_f32_16x16x32_bf16 v[68:71], v[120:123], v[180:183], v[68:71]
	v_mfma_f32_16x16x32_bf16 v[72:75], v[108:111], v[188:191], v[72:75]
	v_mfma_f32_16x16x32_bf16 v[76:79], v[120:123], v[188:191], v[76:79]
	v_mfma_f32_16x16x32_bf16 v[48:51], v[116:119], v[156:159], v[48:51]
	v_mfma_f32_16x16x32_bf16 v[52:55], v[124:127], v[156:159], v[52:55]
	v_mfma_f32_16x16x32_bf16 v[56:59], v[116:119], v[164:167], v[56:59]
	v_mfma_f32_16x16x32_bf16 v[60:63], v[124:127], v[164:167], v[60:63]
	v_mfma_f32_16x16x32_bf16 v[64:67], v[116:119], v[184:187], v[64:67]
	v_mfma_f32_16x16x32_bf16 v[68:71], v[124:127], v[184:187], v[68:71]
	v_mfma_f32_16x16x32_bf16 v[72:75], v[116:119], v[192:195], v[72:75]
	v_mfma_f32_16x16x32_bf16 v[76:79], v[124:127], v[192:195], v[76:79]
	s_barrier
	s_mov_b32 m0, s49
	v_lshl_add_u64 v[168:169], s[26:27], 0, v[148:149]
	ds_read_b128 v[196:199], v175
	ds_read_b128 v[200:203], v175 offset:1024
	ds_read_b128 v[204:207], v175 offset:2048
	ds_read_b128 v[208:211], v175 offset:3072
	global_load_lds_dwordx4 v[168:169], off
	s_mov_b32 m0, s50
	v_lshl_add_u64 v[230:231], s[26:27], 0, v[144:145]
	global_load_lds_dwordx4 v[230:231], off
	s_barrier
	s_waitcnt lgkmcnt(0)
	v_mfma_f32_16x16x32_bf16 v[96:99], v[196:199], v[152:155], v[96:99]
	v_mfma_f32_16x16x32_bf16 v[16:19], v[204:207], v[152:155], v[16:19]
	v_mfma_f32_16x16x32_bf16 v[20:23], v[196:199], v[160:163], v[20:23]
	v_mfma_f32_16x16x32_bf16 v[24:27], v[204:207], v[160:163], v[24:27]
	v_mfma_f32_16x16x32_bf16 v[28:31], v[196:199], v[180:183], v[28:31]
	v_mfma_f32_16x16x32_bf16 v[32:35], v[204:207], v[180:183], v[32:35]
	v_mfma_f32_16x16x32_bf16 v[36:39], v[196:199], v[188:191], v[36:39]
	v_mfma_f32_16x16x32_bf16 v[40:43], v[204:207], v[188:191], v[40:43]
	v_mfma_f32_16x16x32_bf16 v[152:155], v[200:203], v[156:159], v[96:99]
	v_mfma_f32_16x16x32_bf16 v[16:19], v[208:211], v[156:159], v[16:19]
	v_mfma_f32_16x16x32_bf16 v[20:23], v[200:203], v[164:167], v[20:23]
	v_mfma_f32_16x16x32_bf16 v[24:27], v[208:211], v[164:167], v[24:27]
	v_mfma_f32_16x16x32_bf16 v[28:31], v[200:203], v[184:187], v[28:31]
	v_mfma_f32_16x16x32_bf16 v[32:35], v[208:211], v[184:187], v[32:35]
	v_mfma_f32_16x16x32_bf16 v[36:39], v[200:203], v[192:195], v[36:39]
	v_mfma_f32_16x16x32_bf16 v[40:43], v[208:211], v[192:195], v[40:43]
	s_mov_b32 m0, s38
	v_lshl_add_u64 v[234:235], s[20:21], 0, v[150:151]
	s_barrier
	ds_read_b128 v[96:99], v174 offset:16384
	ds_read_b128 v[156:159], v174 offset:17408
	ds_read_b128 v[160:163], v174 offset:18432
	ds_read_b128 v[164:167], v174 offset:19456
	ds_read_b128 v[180:183], v174 offset:20480
	ds_read_b128 v[184:187], v174 offset:21504
	ds_read_b128 v[188:191], v174 offset:22528
	ds_read_b128 v[192:195], v174 offset:23552
	global_load_lds_dwordx4 v[234:235], off nt
	s_mov_b32 m0, s39
	v_lshl_add_u64 v[236:237], s[20:21], 0, v[146:147]
	global_load_lds_dwordx4 v[236:237], off nt
	s_barrier
	s_waitcnt lgkmcnt(0)
	v_mfma_f32_16x16x32_bf16 v[88:91], v[108:111], v[96:99], v[88:91]
	v_mfma_f32_16x16x32_bf16 v[112:115], v[120:123], v[96:99], v[112:115]
	v_mfma_f32_16x16x32_bf16 v[136:139], v[108:111], v[180:183], v[136:139]
	v_mfma_f32_16x16x32_bf16 v[140:143], v[120:123], v[180:183], v[140:143]
	v_mfma_f32_16x16x32_bf16 v[0:3], v[108:111], v[188:191], v[0:3]
	v_mfma_f32_16x16x32_bf16 v[4:7], v[120:123], v[188:191], v[4:7]
	v_mfma_f32_16x16x32_bf16 v[128:131], v[108:111], v[160:163], v[128:131]
	v_mfma_f32_16x16x32_bf16 v[132:135], v[120:123], v[160:163], v[132:135]
	v_mfma_f32_16x16x32_bf16 v[88:91], v[116:119], v[156:159], v[88:91]
	v_mfma_f32_16x16x32_bf16 v[112:115], v[124:127], v[156:159], v[112:115]
	v_mfma_f32_16x16x32_bf16 v[136:139], v[116:119], v[184:187], v[136:139]
	v_mfma_f32_16x16x32_bf16 v[140:143], v[124:127], v[184:187], v[140:143]
	v_mfma_f32_16x16x32_bf16 v[0:3], v[116:119], v[192:195], v[0:3]
	v_mfma_f32_16x16x32_bf16 v[4:7], v[124:127], v[192:195], v[4:7]
	v_mfma_f32_16x16x32_bf16 v[212:215], v[116:119], v[164:167], v[128:131]
	v_mfma_f32_16x16x32_bf16 v[216:219], v[124:127], v[164:167], v[132:135]
	s_barrier
	s_add_u32 s24, s26, 0x10000
	s_addc_u32 s25, s27, 0
	s_mov_b32 m0, s19
	v_lshl_add_u64 v[108:109], s[24:25], 0, v[148:149]
	global_load_lds_dwordx4 v[108:109], off
	s_mov_b32 m0, s17
	v_lshl_add_u64 v[108:109], s[24:25], 0, v[144:145]
	global_load_lds_dwordx4 v[108:109], off
	s_waitcnt vmcnt(6)
	s_barrier
	v_mfma_f32_16x16x32_bf16 v[8:11], v[196:199], v[96:99], v[8:11]
	v_mfma_f32_16x16x32_bf16 v[12:15], v[204:207], v[96:99], v[12:15]
	v_mfma_f32_16x16x32_bf16 v[44:47], v[196:199], v[160:163], v[44:47]
	v_mfma_f32_16x16x32_bf16 v[92:95], v[204:207], v[160:163], v[92:95]
	v_mfma_f32_16x16x32_bf16 v[96:99], v[196:199], v[180:183], v[100:103]
	v_mfma_f32_16x16x32_bf16 v[100:103], v[204:207], v[180:183], v[104:107]
	v_mfma_f32_16x16x32_bf16 v[80:83], v[196:199], v[188:191], v[80:83]
	v_mfma_f32_16x16x32_bf16 v[84:87], v[204:207], v[188:191], v[84:87]
	v_mfma_f32_16x16x32_bf16 v[124:127], v[200:203], v[156:159], v[8:11]
	v_mfma_f32_16x16x32_bf16 v[156:159], v[208:211], v[156:159], v[12:15]
	v_mfma_f32_16x16x32_bf16 v[160:163], v[200:203], v[164:167], v[44:47]
	v_mfma_f32_16x16x32_bf16 v[164:167], v[208:211], v[164:167], v[92:95]
	v_mfma_f32_16x16x32_bf16 v[180:183], v[200:203], v[184:187], v[96:99]
	v_mfma_f32_16x16x32_bf16 v[100:103], v[208:211], v[184:187], v[100:103]
	v_mfma_f32_16x16x32_bf16 v[184:187], v[200:203], v[192:195], v[80:83]
	v_mfma_f32_16x16x32_bf16 v[188:191], v[208:211], v[192:195], v[84:87]
	s_barrier
	ds_read_b128 v[8:11], v221
	ds_read_b128 v[12:15], v221 offset:1024
	ds_read_b128 v[44:47], v221 offset:2048
	ds_read_b128 v[192:195], v221 offset:3072
	s_add_u32 s24, s20, 0x40000
	s_addc_u32 s25, s21, 0
	s_mov_b32 m0, s40
	v_lshl_add_u64 v[92:93], s[24:25], 0, v[150:151]
	ds_read_b128 v[80:83], v174 offset:32768
	ds_read_b128 v[84:87], v174 offset:33792
	ds_read_b128 v[104:107], v174 offset:34816
	ds_read_b128 v[196:199], v174 offset:35840
	ds_read_b128 v[108:111], v174 offset:36864
	ds_read_b128 v[200:203], v174 offset:37888
	ds_read_b128 v[204:207], v174 offset:38912
	ds_read_b128 v[208:211], v174 offset:39936
	global_load_lds_dwordx4 v[92:93], off nt
	s_mov_b32 m0, s41
	v_lshl_add_u64 v[92:93], s[24:25], 0, v[146:147]
	global_load_lds_dwordx4 v[92:93], off nt
	s_waitcnt lgkmcnt(8)
	s_barrier
;     __device__ __forceinline__ void epi(const f32x4 (&acc)[2][2][4][2], const Unit& u, int wr, int wc, int fr, int fq) const {
;     ...
;         const int row0 = u.pm * 256 + wr * 64 + fr, col0 = u.pn * 256 + wc * 32 + 8 * fq;
; #pragma unroll
;         for (int ai = 0; ai < 2; ++ai) {
;             u32x4 xo[4][2];
; #pragma unroll
;             for (int m = 0; m < 4; ++m)
; #pragma unroll
;                 for (int bj = 0; bj < 2; ++bj) xo[m][bj] = *(const u32x4*)(xb + (size_t)(row0 + ai * 128 + m * 16) * D + col0 + bj * 128);
	s_waitcnt lgkmcnt(0)
	v_mfma_f32_16x16x32_bf16 v[52:55], v[44:47], v[80:83], v[52:55]
	v_mfma_f32_16x16x32_bf16 v[56:59], v[8:11], v[104:107], v[56:59]
	v_mfma_f32_16x16x32_bf16 v[60:63], v[44:47], v[104:107], v[60:63]
	v_mfma_f32_16x16x32_bf16 v[64:67], v[8:11], v[108:111], v[64:67]
	v_mfma_f32_16x16x32_bf16 v[68:71], v[44:47], v[108:111], v[68:71]
	v_mfma_f32_16x16x32_bf16 v[72:75], v[8:11], v[204:207], v[72:75]
	v_mfma_f32_16x16x32_bf16 v[222:225], v[44:47], v[204:207], v[76:79]
	v_mfma_f32_16x16x32_bf16 v[48:51], v[8:11], v[80:83], v[48:51]
	v_mfma_f32_16x16x32_bf16 v[128:131], v[192:195], v[84:87], v[52:55]
	v_mfma_f32_16x16x32_bf16 v[120:123], v[12:15], v[196:199], v[56:59]
	v_mfma_f32_16x16x32_bf16 v[116:119], v[192:195], v[196:199], v[60:63]
	v_mfma_f32_16x16x32_bf16 v[96:99], v[12:15], v[200:203], v[64:67]
	v_mfma_f32_16x16x32_bf16 v[92:95], v[192:195], v[200:203], v[68:71]
	v_mfma_f32_16x16x32_bf16 v[76:79], v[12:15], v[208:211], v[72:75]
	v_mfma_f32_16x16x32_bf16 v[72:75], v[192:195], v[208:211], v[222:225]
	v_mfma_f32_16x16x32_bf16 v[132:135], v[12:15], v[84:87], v[48:51]
	s_barrier
	s_mov_b32 m0, s53
	v_lshl_add_u64 v[48:49], v[168:169], 0, s[6:7]
	ds_read_b128 v[56:59], v226
	ds_read_b128 v[222:225], v226 offset:1024
	ds_read_b128 v[60:63], v226 offset:2048
	ds_read_b128 v[226:229], v226 offset:3072
	global_load_lds_dwordx4 v[48:49], off
	s_mov_b32 m0, s51
	v_lshl_add_u64 v[48:49], v[230:231], 0, s[6:7]
	global_load_lds_dwordx4 v[48:49], off
	s_barrier
	s_waitcnt lgkmcnt(0)
	v_mfma_f32_16x16x32_bf16 v[48:51], v[56:59], v[80:83], v[152:155]
	v_mfma_f32_16x16x32_bf16 v[16:19], v[60:63], v[80:83], v[16:19]
	v_mfma_f32_16x16x32_bf16 v[20:23], v[56:59], v[104:107], v[20:23]
	v_mfma_f32_16x16x32_bf16 v[24:27], v[60:63], v[104:107], v[24:27]
	v_mfma_f32_16x16x32_bf16 v[28:31], v[56:59], v[108:111], v[28:31]
	v_mfma_f32_16x16x32_bf16 v[32:35], v[60:63], v[108:111], v[32:35]
	v_mfma_f32_16x16x32_bf16 v[36:39], v[56:59], v[204:207], v[36:39]
	v_mfma_f32_16x16x32_bf16 v[40:43], v[60:63], v[204:207], v[40:43]
	v_mfma_f32_16x16x32_bf16 v[204:207], v[222:225], v[84:87], v[48:51]
	v_mfma_f32_16x16x32_bf16 v[230:233], v[226:229], v[84:87], v[16:19]
	v_mfma_f32_16x16x32_bf16 v[108:111], v[222:225], v[196:199], v[20:23]
	v_mfma_f32_16x16x32_bf16 v[104:107], v[226:229], v[196:199], v[24:27]
	v_mfma_f32_16x16x32_bf16 v[84:87], v[222:225], v[200:203], v[28:31]
	v_mfma_f32_16x16x32_bf16 v[80:83], v[226:229], v[200:203], v[32:35]
	v_mfma_f32_16x16x32_bf16 v[68:71], v[222:225], v[208:211], v[36:39]
	v_mfma_f32_16x16x32_bf16 v[64:67], v[226:229], v[208:211], v[40:43]
	s_mov_b32 m0, s43
	v_lshl_add_u64 v[24:25], v[234:235], 0, s[6:7]
	s_barrier
	ds_read_b128 v[16:19], v174 offset:49152
	ds_read_b128 v[20:23], v174 offset:50176
	ds_read_b128 v[32:35], v174 offset:51200
	ds_read_b128 v[152:155], v174 offset:52224
	ds_read_b128 v[36:39], v174 offset:53248
	ds_read_b128 v[196:199], v174 offset:54272
	ds_read_b128 v[200:203], v174 offset:55296
	ds_read_b128 v[208:211], v174 offset:56320
	global_load_lds_dwordx4 v[24:25], off nt
	s_mov_b32 m0, s44
	v_lshl_add_u64 v[24:25], v[236:237], 0, s[6:7]
	global_load_lds_dwordx4 v[24:25], off nt
	s_barrier
	s_waitcnt lgkmcnt(0)
	v_mfma_f32_16x16x32_bf16 v[24:27], v[8:11], v[16:19], v[88:91]
	v_mfma_f32_16x16x32_bf16 v[28:31], v[44:47], v[16:19], v[112:115]
	v_mfma_f32_16x16x32_bf16 v[40:43], v[8:11], v[32:35], v[212:215]
	v_mfma_f32_16x16x32_bf16 v[88:91], v[44:47], v[32:35], v[216:219]
	v_mfma_f32_16x16x32_bf16 v[112:115], v[8:11], v[36:39], v[136:139]
	v_mfma_f32_16x16x32_bf16 v[136:139], v[44:47], v[36:39], v[140:143]
	v_mfma_f32_16x16x32_bf16 v[0:3], v[8:11], v[200:203], v[0:3]
	v_mfma_f32_16x16x32_bf16 v[4:7], v[44:47], v[200:203], v[4:7]
	v_mfma_f32_16x16x32_bf16 v[52:55], v[12:15], v[20:23], v[24:27]
	v_mfma_f32_16x16x32_bf16 v[48:51], v[192:195], v[20:23], v[28:31]
	v_mfma_f32_16x16x32_bf16 v[44:47], v[12:15], v[152:155], v[40:43]
	v_mfma_f32_16x16x32_bf16 v[40:43], v[192:195], v[152:155], v[88:91]
	v_mfma_f32_16x16x32_bf16 v[28:31], v[12:15], v[196:199], v[112:115]
	v_mfma_f32_16x16x32_bf16 v[24:27], v[192:195], v[196:199], v[136:139]
	v_mfma_f32_16x16x32_bf16 v[12:15], v[12:15], v[208:211], v[0:3]
	v_mfma_f32_16x16x32_bf16 v[8:11], v[192:195], v[208:211], v[4:7]
	s_barrier
	s_add_u32 s24, s26, 0x10080
	s_addc_u32 s25, s27, 0
	s_mov_b32 m0, s54
	v_lshl_add_u64 v[0:1], s[24:25], 0, v[148:149]
	global_load_lds_dwordx4 v[0:1], off
	s_mov_b32 m0, s52
	v_lshl_add_u64 v[0:1], s[24:25], 0, v[144:145]
	global_load_lds_dwordx4 v[0:1], off
	s_waitcnt vmcnt(6)
	s_barrier
	v_mfma_f32_16x16x32_bf16 v[0:3], v[56:59], v[16:19], v[124:127]
	v_mfma_f32_16x16x32_bf16 v[4:7], v[60:63], v[16:19], v[156:159]
	v_mfma_f32_16x16x32_bf16 v[16:19], v[56:59], v[32:35], v[160:163]
	v_mfma_f32_16x16x32_bf16 v[32:35], v[60:63], v[32:35], v[164:167]
	v_mfma_f32_16x16x32_bf16 v[88:91], v[56:59], v[36:39], v[180:183]
	v_mfma_f32_16x16x32_bf16 v[100:103], v[60:63], v[36:39], v[100:103]
	v_mfma_f32_16x16x32_bf16 v[112:115], v[56:59], v[200:203], v[184:187]
	v_mfma_f32_16x16x32_bf16 v[124:127], v[60:63], v[200:203], v[188:191]
	v_mfma_f32_16x16x32_bf16 v[60:63], v[222:225], v[20:23], v[0:3]
	v_mfma_f32_16x16x32_bf16 v[56:59], v[226:229], v[20:23], v[4:7]
	v_mfma_f32_16x16x32_bf16 v[36:39], v[222:225], v[152:155], v[16:19]
	v_mfma_f32_16x16x32_bf16 v[32:35], v[226:229], v[152:155], v[32:35]
	v_mfma_f32_16x16x32_bf16 v[20:23], v[222:225], v[196:199], v[88:91]
	v_mfma_f32_16x16x32_bf16 v[16:19], v[226:229], v[196:199], v[100:103]
	v_mfma_f32_16x16x32_bf16 v[4:7], v[222:225], v[208:211], v[112:115]
	v_mfma_f32_16x16x32_bf16 v[0:3], v[226:229], v[208:211], v[124:127]
	v_lshl_or_b32 v152, s45, 8, v172
	v_lshl_add_u32 v156, s8, 8, v170
	v_ashrrev_i32_e32 v153, 31, v152
	v_lshlrev_b64 v[190:191], 1, v[152:153]
	v_ashrrev_i32_e32 v157, 31, v156
	v_lshl_add_u64 v[154:155], s[0:1], 0, v[190:191]
	v_lshlrev_b64 v[192:193], 11, v[156:157]
	v_lshl_add_u64 v[88:89], v[154:155], 0, v[192:193]
	s_barrier
; __device__ __forceinline__ unsigned pk2(float lo, float hi) { unsigned r; asm volatile("v_cvt_pk_bf16_f32 %0, %1, %2" : "=v"(r) : "v"(lo), "v"(hi)); return r; }
; __device__ __forceinline__ unsigned pk2(float lo, float hi) { return f2bf(lo) | (f2bf(hi) << 16); }
;     __device__ __forceinline__ void epi(const f32x4 (&acc)[2][2][4][2], const Unit& u, int wr, int wc, int fr, int fq) const {
;     ...
;         const int row0 = u.pm * 256 + wr * 64 + fr, col0 = u.pn * 256 + wc * 32 + 8 * fq;
; #pragma unroll
;         for (int ai = 0; ai < 2; ++ai) {
;             u32x4 xo[4][2];
; #pragma unroll
;             for (int m = 0; m < 4; ++m)
; #pragma unroll
;                 for (int bj = 0; bj < 2; ++bj) xo[m][bj] = *(const u32x4*)(xb + (size_t)(row0 + ai * 128 + m * 16) * D + col0 + bj * 128);
; #pragma unroll
;             for (int m = 0; m < 4; ++m) {
;                 const int row = row0 + ai * 128 + m * 16; const size_t off = (size_t)row * D + col0; float ss = 0.f;
; #pragma unroll
;                 for (int bj = 0; bj < 2; ++bj) {
;                     const u32x4 o = xo[m][bj]; const f32x4 a0v = acc[ai][bj][m][0], a1v = acc[ai][bj][m][1];
;                     const float v0 = bf_lo(o.x) + coef * a0v[0], v1 = bf_hi(o.x) + coef * a0v[1], v2 = bf_lo(o.y) + coef * a0v[2], v3 = bf_hi(o.y) + coef * a0v[3];
;                     const float v4 = bf_lo(o.z) + coef * a1v[0], v5 = bf_hi(o.z) + coef * a1v[1], v6 = bf_lo(o.w) + coef * a1v[2], v7 = bf_hi(o.w) + coef * a1v[3];
;                     u32x4 w; w.x = pk2(v0, v1); w.y = pk2(v2, v3); w.z = pk2(v4, v5); w.w = pk2(v6, v7);
;                     *(u32x4*)(xb + off + bj * 128) = w;
;                     ss += ((v0 * v0 + v1 * v1) + (v2 * v2 + v3 * v3)) + ((v4 * v4 + v5 * v5) + (v6 * v6 + v7 * v7));
;                 }
;                 ss += __shfl_xor(ss, 16); ss += __shfl_xor(ss, 32);
;                 if (fq == 0) rowss[(size_t)row * 32 + u.pn * 4 + wc] = ss;
;             }
	v_mov_b32_e32 v214, 0x40000
	v_mov_b32_e32 v215, 0
	v_lshl_add_u64 v[212:213], v[88:89], 0, v[214:215]
	v_mov_b32_e32 v214, 0x8000
	global_load_dwordx4 v[182:185], v[88:89], off
	global_load_dwordx4 v[186:189], v[88:89], off offset:256
	v_or_b32_e32 v166, 16, v156
	v_or_b32_e32 v162, 32, v156
	v_or_b32_e32 v158, 48, v156
	v_ashrrev_i32_e32 v167, 31, v166
	v_ashrrev_i32_e32 v163, 31, v162
	v_ashrrev_i32_e32 v159, 31, v158
	v_lshlrev_b64 v[168:169], 11, v[166:167]
	v_lshlrev_b64 v[164:165], 11, v[162:163]
	v_lshlrev_b64 v[160:161], 11, v[158:159]
	v_lshl_add_u64 v[88:89], v[154:155], 0, v[168:169]
	v_lshl_add_u64 v[90:91], v[154:155], 0, v[164:165]
	v_lshl_add_u64 v[180:181], v[154:155], 0, v[160:161]
	global_load_dwordx4 v[140:143], v[88:89], off
	global_load_dwordx4 v[136:139], v[88:89], off offset:256
	global_load_dwordx4 v[124:127], v[90:91], off
	global_load_dwordx4 v[112:115], v[90:91], off offset:256
	global_load_dwordx4 v[100:103], v[180:181], off
	s_nop 0
	global_load_dwordx4 v[88:91], v[180:181], off offset:256
	global_load_dwordx4 v[216:219], v[212:213], off
	global_load_dwordx4 v[222:225], v[212:213], off offset:256
	v_lshl_add_u64 v[212:213], v[212:213], 0, v[214:215]
	global_load_dwordx4 v[226:229], v[212:213], off
	global_load_dwordx4 v[234:237], v[212:213], off offset:256
	v_lshl_add_u64 v[212:213], v[212:213], 0, v[214:215]
	global_load_dwordx4 v[238:241], v[212:213], off
	global_load_dwordx4 v[242:245], v[212:213], off offset:256
	v_lshl_add_u64 v[212:213], v[212:213], 0, v[214:215]
	global_load_dwordx4 v[246:249], v[212:213], off
	global_load_dwordx4 v[250:253], v[212:213], off offset:256
	v_lshl_add_u64 v[192:193], s[0:1], 0, v[192:193]
	v_lshl_add_u64 v[190:191], v[192:193], 0, v[190:191]
	v_cmp_lt_i32_e32 vcc, v177, v178
	s_waitcnt vmcnt(8)
	v_lshlrev_b32_e32 v181, 16, v182
	v_and_b32_e32 v182, 0xffff0000, v182
	v_lshlrev_b32_e32 v192, 16, v183
	v_and_b32_e32 v183, 0xffff0000, v183
	v_lshlrev_b32_e32 v193, 16, v184
	v_and_b32_e32 v184, 0xffff0000, v184
	v_lshlrev_b32_e32 v194, 16, v185
	v_and_b32_e32 v185, 0xffff0000, v185
	v_lshlrev_b32_e32 v195, 16, v186
	v_and_b32_e32 v186, 0xffff0000, v186
	v_lshlrev_b32_e32 v196, 16, v187
	v_and_b32_e32 v187, 0xffff0000, v187
	v_lshlrev_b32_e32 v197, 16, v188
	v_and_b32_e32 v188, 0xffff0000, v188
	v_lshlrev_b32_e32 v198, 16, v189
	v_and_b32_e32 v189, 0xffff0000, v189
	v_add_f32_e32 v133, v133, v182
	v_add_f32_e32 v135, v135, v183
	v_add_f32_e32 v182, v129, v184
	v_add_f32_e32 v131, v131, v185
	v_add_f32_e32 v185, v205, v186
	v_add_f32_e32 v187, v207, v187
	v_add_f32_e32 v188, v231, v188
	v_add_f32_e32 v189, v233, v189
	v_add_f32_e32 v132, v132, v181
	v_add_f32_e32 v134, v134, v192
	v_add_f32_e32 v181, v128, v193
	v_add_f32_e32 v183, v130, v194
	v_add_f32_e32 v184, v204, v195
	v_add_f32_e32 v186, v206, v196
	v_add_f32_e32 v192, v230, v197
	v_add_f32_e32 v193, v232, v198
	v_cvt_pk_bf16_f32 v128, v132, v133
	v_cvt_pk_bf16_f32 v129, v134, v135
	v_mul_f32_e32 v130, v133, v133
	v_mul_f32_e32 v133, v135, v135
	v_mul_f32_e32 v135, v182, v182
	v_mul_f32_e32 v194, v131, v131
	v_mul_f32_e32 v195, v185, v185
	v_mul_f32_e32 v196, v187, v187
	v_mul_f32_e32 v197, v188, v188
	v_mul_f32_e32 v198, v189, v189
	v_fmac_f32_e32 v130, v132, v132
	v_fmac_f32_e32 v133, v134, v134
	v_fmac_f32_e32 v135, v181, v181
	v_fmac_f32_e32 v194, v183, v183
	v_fmac_f32_e32 v195, v184, v184
	v_fmac_f32_e32 v196, v186, v186
	v_fmac_f32_e32 v197, v192, v192
	v_fmac_f32_e32 v198, v193, v193
	v_add_f32_e32 v130, v130, v133
	v_add_f32_e32 v132, v135, v194
	v_add_f32_e32 v133, v195, v196
	v_add_f32_e32 v134, v197, v198
	v_cndmask_b32_e32 v180, v176, v177, vcc
	v_add_f32_e32 v130, v130, v132
	v_add_f32_e32 v132, v133, v134
	v_lshlrev_b32_e32 v180, 2, v180
	v_add_f32_e32 v133, v130, v132
	v_mov_b32_e32 v134, v133
	s_nop 1
	v_permlane16_swap_b32 v134, v133
	v_cmp_lt_i32_e32 vcc, v179, v178
	v_cvt_pk_bf16_f32 v130, v181, v182
	v_cvt_pk_bf16_f32 v131, v183, v131
	global_store_dwordx4 v[190:191], v[128:131], off
	v_cvt_pk_bf16_f32 v132, v184, v185
	s_nop 1
	v_cndmask_b32_e32 v128, v176, v179, vcc
	s_waitcnt lgkmcnt(0)
	v_add_f32_e32 v129, v133, v134
	v_lshlrev_b32_e32 v128, 2, v128
	v_mov_b32_e32 v130, v129
	s_nop 1
	v_permlane32_swap_b32 v130, v129
	v_cvt_pk_bf16_f32 v133, v186, v187
	v_cvt_pk_bf16_f32 v134, v192, v188
	v_cvt_pk_bf16_f32 v135, v193, v189
	global_store_dwordx4 v[190:191], v[132:135], off offset:256
	s_and_saveexec_b64 s[24:25], s[4:5]
	s_cbranch_execz .LBB0_1672
	s_waitcnt lgkmcnt(0)
	v_add_f32_e32 v129, v129, v130
	s_lshl_b32 s26, s45, 2
	v_lshlrev_b64 v[130:131], 7, v[156:157]
	s_ashr_i32 s27, s26, 31
	v_lshl_add_u64 v[130:131], s[2:3], 0, v[130:131]
	v_lshl_add_u64 v[130:131], s[26:27], 2, v[130:131]
	s_lshl_b32 s8, s42, 2
	v_lshl_add_u64 v[130:131], v[130:131], 0, s[8:9]
	global_store_dword v[130:131], v129, off
